# GEMM tile-loop headers (FFN1-in, in_proj, FFN2-in): next-unit mapping by closed form pm=(L&7)*8+((L>>3)&7), pn=L>>6 instead of generic division chain, on top of v23
# baseline (speedup 1.0000x reference)
;     __device__ bool next(int i, Unit& u) const { Unit b; if (!so.next(i >> 2, b)) return false; const int sub = i & 3; u.pm = b.pm; u.pn = sub * 4 + b.pn; u.acol = sub * 512; u.ord = i; return true; }
;     __device__ bool next(int i, Unit& u) const {
;         const long L = (long)i * G + c; if (L >= nwg) return false;
;         int wgid = (int)L; { const int q = nwg / NXCD, r = nwg % NXCD, xcd = wgid % NXCD, off = wgid / NXCD; wgid = (xcd < r ? xcd * (q + 1) : r * (q + 1) + (xcd - r) * q) + off; }
;         const int nig = WGM * nN, gid = wgid / nig, fm = gid * WGM, gsz = (nM - fm) < WGM ? (nM - fm) : WGM;
;         u.pm = fm + ((wgid % nig) % gsz); u.pn = (wgid % nig) / gsz; u.acol = 0; u.ord = i; return true;
.LBB0_228:
	s_add_i32 s56, s56, 1
	s_mul_i32 s36, s56, s34
	s_mul_hi_u32 s37, s56, s94
	s_add_i32 s37, s37, s36
	s_mul_i32 s36, s56, s94
	s_add_u32 s42, s36, s71
	s_addc_u32 s43, s37, s48
	v_cmp_gt_i64_e32 vcc, s[42:43], v[184:185]
	v_cmp_lt_i64_e64 s[36:37], s[42:43], v[186:187]
	s_cbranch_vccnz .LBB0_230
	s_mov_b32 s57, s56
	s_and_b32 s40, s42, 7
	s_lshl_b32 s40, s40, 3
	s_bfe_u32 s38, s42, 0x30003
	s_or_b32 s40, s40, s38
	s_lshr_b32 s38, s42, 6

;     __device__ bool next(int i, Unit& u) const { Unit b; if (!so.next(i >> 2, b)) return false; const int sub = i & 3; u.pm = b.pm; u.pn = sub * 4 + b.pn; u.acol = sub * 512; u.ord = i; return true; }
;     __device__ bool next(int i, Unit& u) const {
;         const long L = (long)i * G + c; if (L >= nwg) return false;
;         int wgid = (int)L; { const int q = nwg / NXCD, r = nwg % NXCD, xcd = wgid % NXCD, off = wgid / NXCD; wgid = (xcd < r ? xcd * (q + 1) : r * (q + 1) + (xcd - r) * q) + off; }
;         const int nig = WGM * nN, gid = wgid / nig, fm = gid * WGM, gsz = (nM - fm) < WGM ? (nM - fm) : WGM;
;         u.pm = fm + ((wgid % nig) % gsz); u.pn = (wgid % nig) / gsz; u.acol = 0; u.ord = i; return true;
.LBB0_432:
	s_add_i32 s57, s57, 1
	s_mul_i32 s28, s57, s34
	s_mul_hi_u32 s29, s57, s94
	s_add_i32 s29, s29, s28
	s_mul_i32 s28, s57, s94
	s_add_u32 s28, s28, s71
	s_addc_u32 s29, s29, s48
	v_cmp_gt_i64_e32 vcc, s[28:29], v[192:193]
	s_mov_b64 s[88:89], s[64:65]
	v_cmp_lt_i64_e64 s[36:37], s[28:29], v[194:195]
	s_cbranch_vccnz .LBB0_434
	s_mov_b32 s58, s57
	s_and_b32 s42, s28, 7
	s_lshl_b32 s42, s42, 3
	s_bfe_u32 s40, s28, 0x30003
	s_or_b32 s42, s42, s40
	s_lshr_b32 s40, s28, 6

;     __device__ bool next(int i, Unit& u) const { Unit b; if (!so.next(i >> 2, b)) return false; const int sub = i & 3; u.pm = b.pm; u.pn = sub * 4 + b.pn; u.acol = sub * 512; u.ord = i; return true; }
;     __device__ bool next(int i, Unit& u) const {
;         const long L = (long)i * G + c; if (L >= nwg) return false;
;         int wgid = (int)L; { const int q = nwg / NXCD, r = nwg % NXCD, xcd = wgid % NXCD, off = wgid / NXCD; wgid = (xcd < r ? xcd * (q + 1) : r * (q + 1) + (xcd - r) * q) + off; }
;         const int nig = WGM * nN, gid = wgid / nig, fm = gid * WGM, gsz = (nM - fm) < WGM ? (nM - fm) : WGM;
;         u.pm = fm + ((wgid % nig) % gsz); u.pn = (wgid % nig) / gsz; u.acol = 0; u.ord = i; return true;
.LBB0_2333:
	s_add_i32 s56, s56, 1
	s_mul_i32 s27, s56, s34
	s_mul_hi_u32 s36, s56, s94
	s_add_i32 s36, s36, s27
	s_mul_i32 s27, s56, s94
	s_add_u32 s40, s27, s71
	s_addc_u32 s41, s36, s46
	v_cmp_gt_i64_e32 vcc, s[40:41], v[184:185]
	s_mov_b64 s[88:89], s[64:65]
	v_cmp_lt_i64_e64 s[36:37], s[40:41], v[186:187]
	s_cbranch_vccnz .LBB0_2335
	s_mov_b32 s57, s56
	s_and_b32 s38, s40, 7
	s_lshl_b32 s38, s38, 3
	s_bfe_u32 s26, s40, 0x30003
	s_or_b32 s38, s38, s26
	s_lshr_b32 s26, s40, 6
